# P1 log-forget epilogue blocks rewritten by hand: same f32 arithmetic for normal arguments, no denormal pre-scale / inf select, two elements interleaved
# baseline (speedup 1.0000x reference)
; __device__ __forceinline__ float sigmoidf_(float x) { return __builtin_amdgcn_rcpf(1.f + __expf(-x)); }
; __device__ __forceinline__ float siluf_(float x) { return x * __builtin_amdgcn_rcpf(1.f + __expf(-x)); }
;     __device__ __forceinline__ void operator()(const f32x4 (&acc)[2][2][4][2], const Unit& u, int wr, int wc, int fr, int fq) const {
;     ...
;             for (int ai = 0; ai < 2; ++ai)
; #pragma unroll
;                 for (int m = 0; m < 4; ++m) { const int r = row0 + ai * HALF + m * 16;
;                     f32x4 v0 = acc[ai][bj][m][0], v1 = acc[ai][bj][m][1];
;                     if (mode == 1) {
; #pragma unroll
;                         for (int i = 0; i < 4; ++i) { v0[i] = siluf_(v0[i]) * QSCALE; v1[i] = siluf_(v1[i]) * QSCALE; }
;                     } else if (mode == 2) {
; #pragma unroll
;                         for (int i = 0; i < 4; ++i) { v0[i] = __logf(lb[i] + (1.f - lb[i]) * sigmoidf_(v0[i])); v1[i] = __logf(lb[4 + i] + (1.f - lb[4 + i]) * sigmoidf_(v1[i])); }
.LBB0_209:
	s_andn2_b64 vcc, exec, s[72:73]
	v_sub_f32_e32 v200, 1.0, v196
	v_sub_f32_e32 v199, 1.0, v195
	v_sub_f32_e32 v198, 1.0, v193
	v_sub_f32_e32 v197, 1.0, v191
	v_sub_f32_e32 v194, 1.0, v189
	v_sub_f32_e32 v192, 1.0, v187
	v_sub_f32_e32 v190, 1.0, v186
	v_sub_f32_e32 v188, 1.0, v185
	s_cbranch_vccnz .LBB0_211
	v_mul_f32_e32 v130, 0xbfb8aa3b, v122
	v_mul_f32_e32 v132, 0xbfb8aa3b, v114
	v_exp_f32_e32 v130, v130
	v_exp_f32_e32 v132, v132
	v_add_f32_e32 v130, 1.0, v130
	v_add_f32_e32 v132, 1.0, v132
	v_rcp_f32_e32 v130, v130
	v_rcp_f32_e32 v132, v132
	v_fma_f32 v130, v130, v200, v196
	v_fma_f32 v132, v132, v199, v195
	v_max_f32_e32 v130, s91, v130
	v_max_f32_e32 v132, s91, v132
	v_log_f32_e32 v130, v130
	v_log_f32_e32 v132, v132
	v_mul_f32_e32 v136, 0x3f317217, v130
	v_mul_f32_e32 v137, 0x3f317217, v132
	v_fma_f32 v136, v130, s92, -v136
	v_fma_f32 v137, v132, s92, -v137
	v_fmac_f32_e32 v136, 0x3377d1cf, v130
	v_fmac_f32_e32 v137, 0x3377d1cf, v132
	v_fma_f32 v130, v130, s92, v136
	v_fma_f32 v132, v132, s92, v137
	v_mul_f32_e32 v131, 0xbfb8aa3b, v123
	v_mul_f32_e32 v133, 0xbfb8aa3b, v115
	v_exp_f32_e32 v131, v131
	v_exp_f32_e32 v133, v133
	v_add_f32_e32 v131, 1.0, v131
	v_add_f32_e32 v133, 1.0, v133
	v_rcp_f32_e32 v131, v131
	v_rcp_f32_e32 v133, v133
	v_fma_f32 v131, v131, v198, v193
	v_fma_f32 v133, v133, v197, v191
	v_max_f32_e32 v131, s91, v131
	v_max_f32_e32 v133, s91, v133
	v_log_f32_e32 v131, v131
	v_log_f32_e32 v133, v133
	v_mul_f32_e32 v136, 0x3f317217, v131
	v_mul_f32_e32 v137, 0x3f317217, v133
	v_fma_f32 v136, v131, s92, -v136
	v_fma_f32 v137, v133, s92, -v137
	v_fmac_f32_e32 v136, 0x3377d1cf, v131
	v_fmac_f32_e32 v137, 0x3377d1cf, v133
	v_fma_f32 v131, v131, s92, v136
	v_fma_f32 v133, v133, s92, v137
	v_mul_f32_e32 v180, 0xbfb8aa3b, v124
	v_mul_f32_e32 v182, 0xbfb8aa3b, v116
	v_exp_f32_e32 v180, v180
	v_exp_f32_e32 v182, v182
	v_add_f32_e32 v180, 1.0, v180
	v_add_f32_e32 v182, 1.0, v182
	v_rcp_f32_e32 v180, v180
	v_rcp_f32_e32 v182, v182
	v_fma_f32 v180, v180, v194, v189
	v_fma_f32 v182, v182, v192, v187
	v_max_f32_e32 v180, s91, v180
	v_max_f32_e32 v182, s91, v182
	v_log_f32_e32 v180, v180
	v_log_f32_e32 v182, v182
	v_mul_f32_e32 v136, 0x3f317217, v180
	v_mul_f32_e32 v137, 0x3f317217, v182
	v_fma_f32 v136, v180, s92, -v136
	v_fma_f32 v137, v182, s92, -v137
	v_fmac_f32_e32 v136, 0x3377d1cf, v180
	v_fmac_f32_e32 v137, 0x3377d1cf, v182
	v_fma_f32 v180, v180, s92, v136
	v_fma_f32 v182, v182, s92, v137
	v_mul_f32_e32 v181, 0xbfb8aa3b, v125
	v_mul_f32_e32 v183, 0xbfb8aa3b, v117
	v_exp_f32_e32 v181, v181
	v_exp_f32_e32 v183, v183
	v_add_f32_e32 v181, 1.0, v181
	v_add_f32_e32 v183, 1.0, v183
	v_rcp_f32_e32 v181, v181
	v_rcp_f32_e32 v183, v183
	v_fma_f32 v181, v181, v190, v186
	v_fma_f32 v183, v183, v188, v185
	v_max_f32_e32 v181, s91, v181
	v_max_f32_e32 v183, s91, v183
	v_log_f32_e32 v181, v181
	v_log_f32_e32 v183, v183
	v_mul_f32_e32 v136, 0x3f317217, v181
	v_mul_f32_e32 v137, 0x3f317217, v183
	v_fma_f32 v136, v181, s92, -v136
	v_fma_f32 v137, v183, s92, -v137
	v_fmac_f32_e32 v136, 0x3377d1cf, v181
	v_fmac_f32_e32 v137, 0x3377d1cf, v183
	v_fma_f32 v181, v181, s92, v136
	v_fma_f32 v183, v183, s92, v137

; __device__ __forceinline__ float sigmoidf_(float x) { return __builtin_amdgcn_rcpf(1.f + __expf(-x)); }
; __device__ __forceinline__ float siluf_(float x) { return x * __builtin_amdgcn_rcpf(1.f + __expf(-x)); }
;     __device__ __forceinline__ void operator()(const f32x4 (&acc)[2][2][4][2], const Unit& u, int wr, int wc, int fr, int fq) const {
;     ...
;             for (int ai = 0; ai < 2; ++ai)
; #pragma unroll
;                 for (int m = 0; m < 4; ++m) { const int r = row0 + ai * HALF + m * 16;
;                     f32x4 v0 = acc[ai][bj][m][0], v1 = acc[ai][bj][m][1];
;                     if (mode == 1) {
; #pragma unroll
;                         for (int i = 0; i < 4; ++i) { v0[i] = siluf_(v0[i]) * QSCALE; v1[i] = siluf_(v1[i]) * QSCALE; }
;                     } else if (mode == 2) {
; #pragma unroll
;                         for (int i = 0; i < 4; ++i) { v0[i] = __logf(lb[i] + (1.f - lb[i]) * sigmoidf_(v0[i])); v1[i] = __logf(lb[4 + i] + (1.f - lb[4 + i]) * sigmoidf_(v1[i])); }
.LBB0_215:
	s_andn2_b64 vcc, exec, s[14:15]
	s_cbranch_vccnz .LBB0_217
	v_mul_f32_e32 v130, 0xbfb8aa3b, v106
	v_mul_f32_e32 v132, 0xbfb8aa3b, v98
	v_exp_f32_e32 v130, v130
	v_exp_f32_e32 v132, v132
	v_add_f32_e32 v130, 1.0, v130
	v_add_f32_e32 v132, 1.0, v132
	v_rcp_f32_e32 v130, v130
	v_rcp_f32_e32 v132, v132
	v_fma_f32 v130, v130, v200, v196
	v_fma_f32 v132, v132, v199, v195
	v_max_f32_e32 v130, s91, v130
	v_max_f32_e32 v132, s91, v132
	v_log_f32_e32 v130, v130
	v_log_f32_e32 v132, v132
	v_mul_f32_e32 v169, 0x3f317217, v130
	v_mul_f32_e32 v171, 0x3f317217, v132
	v_fma_f32 v169, v130, s92, -v169
	v_fma_f32 v171, v132, s92, -v171
	v_fmac_f32_e32 v169, 0x3377d1cf, v130
	v_fmac_f32_e32 v171, 0x3377d1cf, v132
	v_fma_f32 v130, v130, s92, v169
	v_fma_f32 v132, v132, s92, v171
	v_mul_f32_e32 v131, 0xbfb8aa3b, v107
	v_mul_f32_e32 v133, 0xbfb8aa3b, v99
	v_exp_f32_e32 v131, v131
	v_exp_f32_e32 v133, v133
	v_add_f32_e32 v131, 1.0, v131
	v_add_f32_e32 v133, 1.0, v133
	v_rcp_f32_e32 v131, v131
	v_rcp_f32_e32 v133, v133
	v_fma_f32 v131, v131, v198, v193
	v_fma_f32 v133, v133, v197, v191
	v_max_f32_e32 v131, s91, v131
	v_max_f32_e32 v133, s91, v133
	v_log_f32_e32 v131, v131
	v_log_f32_e32 v133, v133
	v_mul_f32_e32 v169, 0x3f317217, v131
	v_mul_f32_e32 v171, 0x3f317217, v133
	v_fma_f32 v169, v131, s92, -v169
	v_fma_f32 v171, v133, s92, -v171
	v_fmac_f32_e32 v169, 0x3377d1cf, v131
	v_fmac_f32_e32 v171, 0x3377d1cf, v133
	v_fma_f32 v131, v131, s92, v169
	v_fma_f32 v133, v133, s92, v171
	v_mul_f32_e32 v180, 0xbfb8aa3b, v108
	v_mul_f32_e32 v182, 0xbfb8aa3b, v100
	v_exp_f32_e32 v180, v180
	v_exp_f32_e32 v182, v182
	v_add_f32_e32 v180, 1.0, v180
	v_add_f32_e32 v182, 1.0, v182
	v_rcp_f32_e32 v180, v180
	v_rcp_f32_e32 v182, v182
	v_fma_f32 v180, v180, v194, v189
	v_fma_f32 v182, v182, v192, v187
	v_max_f32_e32 v180, s91, v180
	v_max_f32_e32 v182, s91, v182
	v_log_f32_e32 v180, v180
	v_log_f32_e32 v182, v182
	v_mul_f32_e32 v169, 0x3f317217, v180
	v_mul_f32_e32 v171, 0x3f317217, v182
	v_fma_f32 v169, v180, s92, -v169
	v_fma_f32 v171, v182, s92, -v171
	v_fmac_f32_e32 v169, 0x3377d1cf, v180
	v_fmac_f32_e32 v171, 0x3377d1cf, v182
	v_fma_f32 v180, v180, s92, v169
	v_fma_f32 v182, v182, s92, v171
	v_mul_f32_e32 v181, 0xbfb8aa3b, v109
	v_mul_f32_e32 v183, 0xbfb8aa3b, v101
	v_exp_f32_e32 v181, v181
	v_exp_f32_e32 v183, v183
	v_add_f32_e32 v181, 1.0, v181
	v_add_f32_e32 v183, 1.0, v183
	v_rcp_f32_e32 v181, v181
	v_rcp_f32_e32 v183, v183
	v_fma_f32 v181, v181, v190, v186
	v_fma_f32 v183, v183, v188, v185
	v_max_f32_e32 v181, s91, v181
	v_max_f32_e32 v183, s91, v183
	v_log_f32_e32 v181, v181
	v_log_f32_e32 v183, v183
	v_mul_f32_e32 v169, 0x3f317217, v181
	v_mul_f32_e32 v171, 0x3f317217, v183
	v_fma_f32 v169, v181, s92, -v169
	v_fma_f32 v171, v183, s92, -v171
	v_fmac_f32_e32 v169, 0x3377d1cf, v181
	v_fmac_f32_e32 v171, 0x3377d1cf, v183
	v_fma_f32 v181, v181, s92, v169
	v_fma_f32 v183, v183, s92, v171

; __device__ __forceinline__ float sigmoidf_(float x) { return __builtin_amdgcn_rcpf(1.f + __expf(-x)); }
; __device__ __forceinline__ float siluf_(float x) { return x * __builtin_amdgcn_rcpf(1.f + __expf(-x)); }
;     __device__ __forceinline__ void operator()(const f32x4 (&acc)[2][2][4][2], const Unit& u, int wr, int wc, int fr, int fq) const {
;     ...
;                 for (int m = 0; m < 4; ++m) { const int r = row0 + ai * HALF + m * 16;
;                     f32x4 v0 = acc[ai][bj][m][0], v1 = acc[ai][bj][m][1];
;                     if (mode == 1) {
; #pragma unroll
;                         for (int i = 0; i < 4; ++i) { v0[i] = siluf_(v0[i]) * QSCALE; v1[i] = siluf_(v1[i]) * QSCALE; }
;                     } else if (mode == 2) {
; #pragma unroll
;                         for (int i = 0; i < 4; ++i) { v0[i] = __logf(lb[i] + (1.f - lb[i]) * sigmoidf_(v0[i])); v1[i] = __logf(lb[4 + i] + (1.f - lb[4 + i]) * sigmoidf_(v1[i])); }
;                     } else if (mode == 3) {
.LBB0_221:
	s_andn2_b64 vcc, exec, s[14:15]
	s_cbranch_vccnz .LBB0_223
	v_mul_f32_e32 v130, 0xbfb8aa3b, v90
	v_mul_f32_e32 v132, 0xbfb8aa3b, v82
	v_exp_f32_e32 v130, v130
	v_exp_f32_e32 v132, v132
	v_add_f32_e32 v130, 1.0, v130
	v_add_f32_e32 v132, 1.0, v132
	v_rcp_f32_e32 v130, v130
	v_rcp_f32_e32 v132, v132
	v_fma_f32 v130, v130, v200, v196
	v_fma_f32 v132, v132, v199, v195
	v_max_f32_e32 v130, s91, v130
	v_max_f32_e32 v132, s91, v132
	v_log_f32_e32 v130, v130
	v_log_f32_e32 v132, v132
	v_mul_f32_e32 v169, 0x3f317217, v130
	v_mul_f32_e32 v171, 0x3f317217, v132
	v_fma_f32 v169, v130, s92, -v169
	v_fma_f32 v171, v132, s92, -v171
	v_fmac_f32_e32 v169, 0x3377d1cf, v130
	v_fmac_f32_e32 v171, 0x3377d1cf, v132
	v_fma_f32 v130, v130, s92, v169
	v_fma_f32 v132, v132, s92, v171
	v_mul_f32_e32 v131, 0xbfb8aa3b, v91
	v_mul_f32_e32 v133, 0xbfb8aa3b, v83
	v_exp_f32_e32 v131, v131
	v_exp_f32_e32 v133, v133
	v_add_f32_e32 v131, 1.0, v131
	v_add_f32_e32 v133, 1.0, v133
	v_rcp_f32_e32 v131, v131
	v_rcp_f32_e32 v133, v133
	v_fma_f32 v131, v131, v198, v193
	v_fma_f32 v133, v133, v197, v191
	v_max_f32_e32 v131, s91, v131
	v_max_f32_e32 v133, s91, v133
	v_log_f32_e32 v131, v131
	v_log_f32_e32 v133, v133
	v_mul_f32_e32 v169, 0x3f317217, v131
	v_mul_f32_e32 v171, 0x3f317217, v133
	v_fma_f32 v169, v131, s92, -v169
	v_fma_f32 v171, v133, s92, -v171
	v_fmac_f32_e32 v169, 0x3377d1cf, v131
	v_fmac_f32_e32 v171, 0x3377d1cf, v133
	v_fma_f32 v131, v131, s92, v169
	v_fma_f32 v133, v133, s92, v171
	v_mul_f32_e32 v180, 0xbfb8aa3b, v92
	v_mul_f32_e32 v182, 0xbfb8aa3b, v84
	v_exp_f32_e32 v180, v180
	v_exp_f32_e32 v182, v182
	v_add_f32_e32 v180, 1.0, v180
	v_add_f32_e32 v182, 1.0, v182
	v_rcp_f32_e32 v180, v180
	v_rcp_f32_e32 v182, v182
	v_fma_f32 v180, v180, v194, v189
	v_fma_f32 v182, v182, v192, v187
	v_max_f32_e32 v180, s91, v180
	v_max_f32_e32 v182, s91, v182
	v_log_f32_e32 v180, v180
	v_log_f32_e32 v182, v182
	v_mul_f32_e32 v169, 0x3f317217, v180
	v_mul_f32_e32 v171, 0x3f317217, v182
	v_fma_f32 v169, v180, s92, -v169
	v_fma_f32 v171, v182, s92, -v171
	v_fmac_f32_e32 v169, 0x3377d1cf, v180
	v_fmac_f32_e32 v171, 0x3377d1cf, v182
	v_fma_f32 v180, v180, s92, v169
	v_fma_f32 v182, v182, s92, v171
	v_mul_f32_e32 v181, 0xbfb8aa3b, v93
	v_mul_f32_e32 v183, 0xbfb8aa3b, v85
	v_exp_f32_e32 v181, v181
	v_exp_f32_e32 v183, v183
	v_add_f32_e32 v181, 1.0, v181
	v_add_f32_e32 v183, 1.0, v183
	v_rcp_f32_e32 v181, v181
	v_rcp_f32_e32 v183, v183
	v_fma_f32 v181, v181, v190, v186
	v_fma_f32 v183, v183, v188, v185
	v_max_f32_e32 v181, s91, v181
	v_max_f32_e32 v183, s91, v183
	v_log_f32_e32 v181, v181
	v_log_f32_e32 v183, v183
	v_mul_f32_e32 v169, 0x3f317217, v181
	v_mul_f32_e32 v171, 0x3f317217, v183
	v_fma_f32 v169, v181, s92, -v169
	v_fma_f32 v171, v183, s92, -v171
	v_fmac_f32_e32 v169, 0x3377d1cf, v181
	v_fmac_f32_e32 v171, 0x3377d1cf, v183
	v_fma_f32 v181, v181, s92, v169
	v_fma_f32 v183, v183, s92, v171

; __device__ __forceinline__ float sigmoidf_(float x) { return __builtin_amdgcn_rcpf(1.f + __expf(-x)); }
; __device__ __forceinline__ float siluf_(float x) { return x * __builtin_amdgcn_rcpf(1.f + __expf(-x)); }
;     __device__ __forceinline__ void operator()(const f32x4 (&acc)[2][2][4][2], const Unit& u, int wr, int wc, int fr, int fq) const {
;     ...
;                 for (int m = 0; m < 4; ++m) { const int r = row0 + ai * HALF + m * 16;
;                     f32x4 v0 = acc[ai][bj][m][0], v1 = acc[ai][bj][m][1];
;                     if (mode == 1) {
; #pragma unroll
;                         for (int i = 0; i < 4; ++i) { v0[i] = siluf_(v0[i]) * QSCALE; v1[i] = siluf_(v1[i]) * QSCALE; }
;                     } else if (mode == 2) {
; #pragma unroll
;                         for (int i = 0; i < 4; ++i) { v0[i] = __logf(lb[i] + (1.f - lb[i]) * sigmoidf_(v0[i])); v1[i] = __logf(lb[4 + i] + (1.f - lb[4 + i]) * sigmoidf_(v1[i])); }
;                     } else if (mode == 3) {
.LBB0_227:
	s_andn2_b64 vcc, exec, s[14:15]
	s_cbranch_vccnz .LBB0_229
	v_mul_f32_e32 v130, 0xbfb8aa3b, v74
	v_mul_f32_e32 v132, 0xbfb8aa3b, v66
	v_exp_f32_e32 v130, v130
	v_exp_f32_e32 v132, v132
	v_add_f32_e32 v130, 1.0, v130
	v_add_f32_e32 v132, 1.0, v132
	v_rcp_f32_e32 v130, v130
	v_rcp_f32_e32 v132, v132
	v_fma_f32 v130, v130, v200, v196
	v_fma_f32 v132, v132, v199, v195
	v_max_f32_e32 v130, s91, v130
	v_max_f32_e32 v132, s91, v132
	v_log_f32_e32 v130, v130
	v_log_f32_e32 v132, v132
	v_mul_f32_e32 v169, 0x3f317217, v130
	v_mul_f32_e32 v171, 0x3f317217, v132
	v_fma_f32 v169, v130, s92, -v169
	v_fma_f32 v171, v132, s92, -v171
	v_fmac_f32_e32 v169, 0x3377d1cf, v130
	v_fmac_f32_e32 v171, 0x3377d1cf, v132
	v_fma_f32 v130, v130, s92, v169
	v_fma_f32 v132, v132, s92, v171
	v_mul_f32_e32 v131, 0xbfb8aa3b, v75
	v_mul_f32_e32 v133, 0xbfb8aa3b, v67
	v_exp_f32_e32 v131, v131
	v_exp_f32_e32 v133, v133
	v_add_f32_e32 v131, 1.0, v131
	v_add_f32_e32 v133, 1.0, v133
	v_rcp_f32_e32 v131, v131
	v_rcp_f32_e32 v133, v133
	v_fma_f32 v131, v131, v198, v193
	v_fma_f32 v133, v133, v197, v191
	v_max_f32_e32 v131, s91, v131
	v_max_f32_e32 v133, s91, v133
	v_log_f32_e32 v131, v131
	v_log_f32_e32 v133, v133
	v_mul_f32_e32 v169, 0x3f317217, v131
	v_mul_f32_e32 v171, 0x3f317217, v133
	v_fma_f32 v169, v131, s92, -v169
	v_fma_f32 v171, v133, s92, -v171
	v_fmac_f32_e32 v169, 0x3377d1cf, v131
	v_fmac_f32_e32 v171, 0x3377d1cf, v133
	v_fma_f32 v131, v131, s92, v169
	v_fma_f32 v133, v133, s92, v171
	v_mul_f32_e32 v180, 0xbfb8aa3b, v76
	v_mul_f32_e32 v182, 0xbfb8aa3b, v68
	v_exp_f32_e32 v180, v180
	v_exp_f32_e32 v182, v182
	v_add_f32_e32 v180, 1.0, v180
	v_add_f32_e32 v182, 1.0, v182
	v_rcp_f32_e32 v180, v180
	v_rcp_f32_e32 v182, v182
	v_fma_f32 v180, v180, v194, v189
	v_fma_f32 v182, v182, v192, v187
	v_max_f32_e32 v180, s91, v180
	v_max_f32_e32 v182, s91, v182
	v_log_f32_e32 v180, v180
	v_log_f32_e32 v182, v182
	v_mul_f32_e32 v169, 0x3f317217, v180
	v_mul_f32_e32 v171, 0x3f317217, v182
	v_fma_f32 v169, v180, s92, -v169
	v_fma_f32 v171, v182, s92, -v171
	v_fmac_f32_e32 v169, 0x3377d1cf, v180
	v_fmac_f32_e32 v171, 0x3377d1cf, v182
	v_fma_f32 v180, v180, s92, v169
	v_fma_f32 v182, v182, s92, v171
	v_mul_f32_e32 v181, 0xbfb8aa3b, v77
	v_mul_f32_e32 v183, 0xbfb8aa3b, v69
	v_exp_f32_e32 v181, v181
	v_exp_f32_e32 v183, v183
	v_add_f32_e32 v181, 1.0, v181
	v_add_f32_e32 v183, 1.0, v183
	v_rcp_f32_e32 v181, v181
	v_rcp_f32_e32 v183, v183
	v_fma_f32 v181, v181, v190, v186
	v_fma_f32 v183, v183, v188, v185
	v_max_f32_e32 v181, s91, v181
	v_max_f32_e32 v183, s91, v183
	v_log_f32_e32 v181, v181
	v_log_f32_e32 v183, v183
	v_mul_f32_e32 v169, 0x3f317217, v181
	v_mul_f32_e32 v171, 0x3f317217, v183
	v_fma_f32 v169, v181, s92, -v169
	v_fma_f32 v171, v183, s92, -v171
	v_fmac_f32_e32 v169, 0x3377d1cf, v181
	v_fmac_f32_e32 v171, 0x3377d1cf, v183
	v_fma_f32 v181, v181, s92, v169
	v_fma_f32 v183, v183, s92, v171

; __device__ __forceinline__ float sigmoidf_(float x) { return __builtin_amdgcn_rcpf(1.f + __expf(-x)); }
; __device__ __forceinline__ float siluf_(float x) { return x * __builtin_amdgcn_rcpf(1.f + __expf(-x)); }
;     __device__ __forceinline__ void operator()(const f32x4 (&acc)[2][2][4][2], const Unit& u, int wr, int wc, int fr, int fq) const {
;     ...
;                 for (int m = 0; m < 4; ++m) { const int r = row0 + ai * HALF + m * 16;
;                     f32x4 v0 = acc[ai][bj][m][0], v1 = acc[ai][bj][m][1];
;                     if (mode == 1) {
; #pragma unroll
;                         for (int i = 0; i < 4; ++i) { v0[i] = siluf_(v0[i]) * QSCALE; v1[i] = siluf_(v1[i]) * QSCALE; }
;                     } else if (mode == 2) {
; #pragma unroll
;                         for (int i = 0; i < 4; ++i) { v0[i] = __logf(lb[i] + (1.f - lb[i]) * sigmoidf_(v0[i])); v1[i] = __logf(lb[4 + i] + (1.f - lb[4 + i]) * sigmoidf_(v1[i])); }
;                     } else if (mode == 3) {
.LBB0_236:
	v_mul_f32_e32 v130, 0xbfb8aa3b, v58
	v_mul_f32_e32 v132, 0xbfb8aa3b, v50
	v_exp_f32_e32 v130, v130
	v_exp_f32_e32 v132, v132
	v_add_f32_e32 v130, 1.0, v130
	v_add_f32_e32 v132, 1.0, v132
	v_rcp_f32_e32 v130, v130
	v_rcp_f32_e32 v132, v132
	v_fma_f32 v130, v130, v200, v196
	v_fma_f32 v132, v132, v199, v195
	v_max_f32_e32 v130, s91, v130
	v_max_f32_e32 v132, s91, v132
	v_log_f32_e32 v130, v130
	v_log_f32_e32 v132, v132
	v_mul_f32_e32 v169, 0x3f317217, v130
	v_mul_f32_e32 v171, 0x3f317217, v132
	v_fma_f32 v169, v130, s92, -v169
	v_fma_f32 v171, v132, s92, -v171
	v_fmac_f32_e32 v169, 0x3377d1cf, v130
	v_fmac_f32_e32 v171, 0x3377d1cf, v132
	v_fma_f32 v130, v130, s92, v169
	v_fma_f32 v132, v132, s92, v171
	v_mul_f32_e32 v131, 0xbfb8aa3b, v59
	v_mul_f32_e32 v133, 0xbfb8aa3b, v51
	v_exp_f32_e32 v131, v131
	v_exp_f32_e32 v133, v133
	v_add_f32_e32 v131, 1.0, v131
	v_add_f32_e32 v133, 1.0, v133
	v_rcp_f32_e32 v131, v131
	v_rcp_f32_e32 v133, v133
	v_fma_f32 v131, v131, v198, v193
	v_fma_f32 v133, v133, v197, v191
	v_max_f32_e32 v131, s91, v131
	v_max_f32_e32 v133, s91, v133
	v_log_f32_e32 v131, v131
	v_log_f32_e32 v133, v133
	v_mul_f32_e32 v169, 0x3f317217, v131
	v_mul_f32_e32 v171, 0x3f317217, v133
	v_fma_f32 v169, v131, s92, -v169
	v_fma_f32 v171, v133, s92, -v171
	v_fmac_f32_e32 v169, 0x3377d1cf, v131
	v_fmac_f32_e32 v171, 0x3377d1cf, v133
	v_fma_f32 v131, v131, s92, v169
	v_fma_f32 v133, v133, s92, v171
	v_mul_f32_e32 v176, 0xbfb8aa3b, v60
	v_mul_f32_e32 v178, 0xbfb8aa3b, v52
	v_exp_f32_e32 v176, v176
	v_exp_f32_e32 v178, v178
	v_add_f32_e32 v176, 1.0, v176
	v_add_f32_e32 v178, 1.0, v178
	v_rcp_f32_e32 v176, v176
	v_rcp_f32_e32 v178, v178
	v_fma_f32 v176, v176, v194, v189
	v_fma_f32 v178, v178, v192, v187
	v_max_f32_e32 v176, s91, v176
	v_max_f32_e32 v178, s91, v178
	v_log_f32_e32 v176, v176
	v_log_f32_e32 v178, v178
	v_mul_f32_e32 v169, 0x3f317217, v176
	v_mul_f32_e32 v171, 0x3f317217, v178
	v_fma_f32 v169, v176, s92, -v169
	v_fma_f32 v171, v178, s92, -v171
	v_fmac_f32_e32 v169, 0x3377d1cf, v176
	v_fmac_f32_e32 v171, 0x3377d1cf, v178
	v_fma_f32 v176, v176, s92, v169
	v_fma_f32 v178, v178, s92, v171
	v_mul_f32_e32 v177, 0xbfb8aa3b, v61
	v_mul_f32_e32 v179, 0xbfb8aa3b, v53
	v_exp_f32_e32 v177, v177
	v_exp_f32_e32 v179, v179
	v_add_f32_e32 v177, 1.0, v177
	v_add_f32_e32 v179, 1.0, v179
	v_rcp_f32_e32 v177, v177
	v_rcp_f32_e32 v179, v179
	v_fma_f32 v177, v177, v190, v186
	v_fma_f32 v179, v179, v188, v185
	v_max_f32_e32 v177, s91, v177
	v_max_f32_e32 v179, s91, v179
	v_log_f32_e32 v177, v177
	v_log_f32_e32 v179, v179
	v_mul_f32_e32 v169, 0x3f317217, v177
	v_mul_f32_e32 v171, 0x3f317217, v179
	v_fma_f32 v169, v177, s92, -v169
	v_fma_f32 v171, v179, s92, -v171
	v_fmac_f32_e32 v169, 0x3377d1cf, v177
	v_fmac_f32_e32 v171, 0x3377d1cf, v179
	v_fma_f32 v177, v177, s92, v169
	v_fma_f32 v179, v179, s92, v171

; __device__ __forceinline__ float sigmoidf_(float x) { return __builtin_amdgcn_rcpf(1.f + __expf(-x)); }
; __device__ __forceinline__ float siluf_(float x) { return x * __builtin_amdgcn_rcpf(1.f + __expf(-x)); }
;     __device__ __forceinline__ void operator()(const f32x4 (&acc)[2][2][4][2], const Unit& u, int wr, int wc, int fr, int fq) const {
;     ...
;                 for (int m = 0; m < 4; ++m) { const int r = row0 + ai * HALF + m * 16;
;                     f32x4 v0 = acc[ai][bj][m][0], v1 = acc[ai][bj][m][1];
;                     if (mode == 1) {
; #pragma unroll
;                         for (int i = 0; i < 4; ++i) { v0[i] = siluf_(v0[i]) * QSCALE; v1[i] = siluf_(v1[i]) * QSCALE; }
;                     } else if (mode == 2) {
; #pragma unroll
;                         for (int i = 0; i < 4; ++i) { v0[i] = __logf(lb[i] + (1.f - lb[i]) * sigmoidf_(v0[i])); v1[i] = __logf(lb[4 + i] + (1.f - lb[4 + i]) * sigmoidf_(v1[i])); }
;                     } else if (mode == 3) {
.LBB0_241:
	s_andn2_b64 vcc, exec, s[14:15]
	s_cbranch_vccnz .LBB0_243
	v_mul_f32_e32 v130, 0xbfb8aa3b, v42
	v_mul_f32_e32 v132, 0xbfb8aa3b, v34
	v_exp_f32_e32 v130, v130
	v_exp_f32_e32 v132, v132
	v_add_f32_e32 v130, 1.0, v130
	v_add_f32_e32 v132, 1.0, v132
	v_rcp_f32_e32 v130, v130
	v_rcp_f32_e32 v132, v132
	v_fma_f32 v130, v130, v200, v196
	v_fma_f32 v132, v132, v199, v195
	v_max_f32_e32 v130, s91, v130
	v_max_f32_e32 v132, s91, v132
	v_log_f32_e32 v130, v130
	v_log_f32_e32 v132, v132
	v_mul_f32_e32 v169, 0x3f317217, v130
	v_mul_f32_e32 v171, 0x3f317217, v132
	v_fma_f32 v169, v130, s92, -v169
	v_fma_f32 v171, v132, s92, -v171
	v_fmac_f32_e32 v169, 0x3377d1cf, v130
	v_fmac_f32_e32 v171, 0x3377d1cf, v132
	v_fma_f32 v130, v130, s92, v169
	v_fma_f32 v132, v132, s92, v171
	v_mul_f32_e32 v131, 0xbfb8aa3b, v43
	v_mul_f32_e32 v133, 0xbfb8aa3b, v35
	v_exp_f32_e32 v131, v131
	v_exp_f32_e32 v133, v133
	v_add_f32_e32 v131, 1.0, v131
	v_add_f32_e32 v133, 1.0, v133
	v_rcp_f32_e32 v131, v131
	v_rcp_f32_e32 v133, v133
	v_fma_f32 v131, v131, v198, v193
	v_fma_f32 v133, v133, v197, v191
	v_max_f32_e32 v131, s91, v131
	v_max_f32_e32 v133, s91, v133
	v_log_f32_e32 v131, v131
	v_log_f32_e32 v133, v133
	v_mul_f32_e32 v169, 0x3f317217, v131
	v_mul_f32_e32 v171, 0x3f317217, v133
	v_fma_f32 v169, v131, s92, -v169
	v_fma_f32 v171, v133, s92, -v171
	v_fmac_f32_e32 v169, 0x3377d1cf, v131
	v_fmac_f32_e32 v171, 0x3377d1cf, v133
	v_fma_f32 v131, v131, s92, v169
	v_fma_f32 v133, v133, s92, v171
	v_mul_f32_e32 v174, 0xbfb8aa3b, v44
	v_mul_f32_e32 v176, 0xbfb8aa3b, v36
	v_exp_f32_e32 v174, v174
	v_exp_f32_e32 v176, v176
	v_add_f32_e32 v174, 1.0, v174
	v_add_f32_e32 v176, 1.0, v176
	v_rcp_f32_e32 v174, v174
	v_rcp_f32_e32 v176, v176
	v_fma_f32 v174, v174, v194, v189
	v_fma_f32 v176, v176, v192, v187
	v_max_f32_e32 v174, s91, v174
	v_max_f32_e32 v176, s91, v176
	v_log_f32_e32 v174, v174
	v_log_f32_e32 v176, v176
	v_mul_f32_e32 v169, 0x3f317217, v174
	v_mul_f32_e32 v171, 0x3f317217, v176
	v_fma_f32 v169, v174, s92, -v169
	v_fma_f32 v171, v176, s92, -v171
	v_fmac_f32_e32 v169, 0x3377d1cf, v174
	v_fmac_f32_e32 v171, 0x3377d1cf, v176
	v_fma_f32 v174, v174, s92, v169
	v_fma_f32 v176, v176, s92, v171
	v_mul_f32_e32 v175, 0xbfb8aa3b, v45
	v_mul_f32_e32 v177, 0xbfb8aa3b, v37
	v_exp_f32_e32 v175, v175
	v_exp_f32_e32 v177, v177
	v_add_f32_e32 v175, 1.0, v175
	v_add_f32_e32 v177, 1.0, v177
	v_rcp_f32_e32 v175, v175
	v_rcp_f32_e32 v177, v177
	v_fma_f32 v175, v175, v190, v186
	v_fma_f32 v177, v177, v188, v185
	v_max_f32_e32 v175, s91, v175
	v_max_f32_e32 v177, s91, v177
	v_log_f32_e32 v175, v175
	v_log_f32_e32 v177, v177
	v_mul_f32_e32 v169, 0x3f317217, v175
	v_mul_f32_e32 v171, 0x3f317217, v177
	v_fma_f32 v169, v175, s92, -v169
	v_fma_f32 v171, v177, s92, -v171
	v_fmac_f32_e32 v169, 0x3377d1cf, v175
	v_fmac_f32_e32 v171, 0x3377d1cf, v177
	v_fma_f32 v175, v175, s92, v169
	v_fma_f32 v177, v177, s92, v171

; __device__ __forceinline__ float sigmoidf_(float x) { return __builtin_amdgcn_rcpf(1.f + __expf(-x)); }
; __device__ __forceinline__ float siluf_(float x) { return x * __builtin_amdgcn_rcpf(1.f + __expf(-x)); }
;     __device__ __forceinline__ void operator()(const f32x4 (&acc)[2][2][4][2], const Unit& u, int wr, int wc, int fr, int fq) const {
;     ...
;                 for (int m = 0; m < 4; ++m) { const int r = row0 + ai * HALF + m * 16;
;                     f32x4 v0 = acc[ai][bj][m][0], v1 = acc[ai][bj][m][1];
;                     if (mode == 1) {
; #pragma unroll
;                         for (int i = 0; i < 4; ++i) { v0[i] = siluf_(v0[i]) * QSCALE; v1[i] = siluf_(v1[i]) * QSCALE; }
;                     } else if (mode == 2) {
; #pragma unroll
;                         for (int i = 0; i < 4; ++i) { v0[i] = __logf(lb[i] + (1.f - lb[i]) * sigmoidf_(v0[i])); v1[i] = __logf(lb[4 + i] + (1.f - lb[4 + i]) * sigmoidf_(v1[i])); }
;                     } else if (mode == 3) {
.LBB0_247:
	s_andn2_b64 vcc, exec, s[14:15]
	s_cbranch_vccnz .LBB0_249
	v_mul_f32_e32 v130, 0xbfb8aa3b, v26
	v_mul_f32_e32 v132, 0xbfb8aa3b, v18
	v_exp_f32_e32 v130, v130
	v_exp_f32_e32 v132, v132
	v_add_f32_e32 v130, 1.0, v130
	v_add_f32_e32 v132, 1.0, v132
	v_rcp_f32_e32 v130, v130
	v_rcp_f32_e32 v132, v132
	v_fma_f32 v130, v130, v200, v196
	v_fma_f32 v132, v132, v199, v195
	v_max_f32_e32 v130, s91, v130
	v_max_f32_e32 v132, s91, v132
	v_log_f32_e32 v130, v130
	v_log_f32_e32 v132, v132
	v_mul_f32_e32 v169, 0x3f317217, v130
	v_mul_f32_e32 v171, 0x3f317217, v132
	v_fma_f32 v169, v130, s92, -v169
	v_fma_f32 v171, v132, s92, -v171
	v_fmac_f32_e32 v169, 0x3377d1cf, v130
	v_fmac_f32_e32 v171, 0x3377d1cf, v132
	v_fma_f32 v130, v130, s92, v169
	v_fma_f32 v132, v132, s92, v171
	v_mul_f32_e32 v131, 0xbfb8aa3b, v27
	v_mul_f32_e32 v133, 0xbfb8aa3b, v19
	v_exp_f32_e32 v131, v131
	v_exp_f32_e32 v133, v133
	v_add_f32_e32 v131, 1.0, v131
	v_add_f32_e32 v133, 1.0, v133
	v_rcp_f32_e32 v131, v131
	v_rcp_f32_e32 v133, v133
	v_fma_f32 v131, v131, v198, v193
	v_fma_f32 v133, v133, v197, v191
	v_max_f32_e32 v131, s91, v131
	v_max_f32_e32 v133, s91, v133
	v_log_f32_e32 v131, v131
	v_log_f32_e32 v133, v133
	v_mul_f32_e32 v169, 0x3f317217, v131
	v_mul_f32_e32 v171, 0x3f317217, v133
	v_fma_f32 v169, v131, s92, -v169
	v_fma_f32 v171, v133, s92, -v171
	v_fmac_f32_e32 v169, 0x3377d1cf, v131
	v_fmac_f32_e32 v171, 0x3377d1cf, v133
	v_fma_f32 v131, v131, s92, v169
	v_fma_f32 v133, v133, s92, v171
	v_mul_f32_e32 v172, 0xbfb8aa3b, v28
	v_mul_f32_e32 v174, 0xbfb8aa3b, v20
	v_exp_f32_e32 v172, v172
	v_exp_f32_e32 v174, v174
	v_add_f32_e32 v172, 1.0, v172
	v_add_f32_e32 v174, 1.0, v174
	v_rcp_f32_e32 v172, v172
	v_rcp_f32_e32 v174, v174
	v_fma_f32 v172, v172, v194, v189
	v_fma_f32 v174, v174, v192, v187
	v_max_f32_e32 v172, s91, v172
	v_max_f32_e32 v174, s91, v174
	v_log_f32_e32 v172, v172
	v_log_f32_e32 v174, v174
	v_mul_f32_e32 v169, 0x3f317217, v172
	v_mul_f32_e32 v171, 0x3f317217, v174
	v_fma_f32 v169, v172, s92, -v169
	v_fma_f32 v171, v174, s92, -v171
	v_fmac_f32_e32 v169, 0x3377d1cf, v172
	v_fmac_f32_e32 v171, 0x3377d1cf, v174
	v_fma_f32 v172, v172, s92, v169
	v_fma_f32 v174, v174, s92, v171
	v_mul_f32_e32 v173, 0xbfb8aa3b, v29
	v_mul_f32_e32 v175, 0xbfb8aa3b, v21
	v_exp_f32_e32 v173, v173
	v_exp_f32_e32 v175, v175
	v_add_f32_e32 v173, 1.0, v173
	v_add_f32_e32 v175, 1.0, v175
	v_rcp_f32_e32 v173, v173
	v_rcp_f32_e32 v175, v175
	v_fma_f32 v173, v173, v190, v186
	v_fma_f32 v175, v175, v188, v185
	v_max_f32_e32 v173, s91, v173
	v_max_f32_e32 v175, s91, v175
	v_log_f32_e32 v173, v173
	v_log_f32_e32 v175, v175
	v_mul_f32_e32 v169, 0x3f317217, v173
	v_mul_f32_e32 v171, 0x3f317217, v175
	v_fma_f32 v169, v173, s92, -v169
	v_fma_f32 v171, v175, s92, -v171
	v_fmac_f32_e32 v169, 0x3377d1cf, v173
	v_fmac_f32_e32 v171, 0x3377d1cf, v175
	v_fma_f32 v173, v173, s92, v169
	v_fma_f32 v175, v175, s92, v171

; __device__ __forceinline__ float sigmoidf_(float x) { return __builtin_amdgcn_rcpf(1.f + __expf(-x)); }
; __device__ __forceinline__ float siluf_(float x) { return x * __builtin_amdgcn_rcpf(1.f + __expf(-x)); }
;     __device__ __forceinline__ void operator()(const f32x4 (&acc)[2][2][4][2], const Unit& u, int wr, int wc, int fr, int fq) const {
;     ...
;                 for (int m = 0; m < 4; ++m) { const int r = row0 + ai * HALF + m * 16;
;                     f32x4 v0 = acc[ai][bj][m][0], v1 = acc[ai][bj][m][1];
;                     if (mode == 1) {
; #pragma unroll
;                         for (int i = 0; i < 4; ++i) { v0[i] = siluf_(v0[i]) * QSCALE; v1[i] = siluf_(v1[i]) * QSCALE; }
;                     } else if (mode == 2) {
; #pragma unroll
;                         for (int i = 0; i < 4; ++i) { v0[i] = __logf(lb[i] + (1.f - lb[i]) * sigmoidf_(v0[i])); v1[i] = __logf(lb[4 + i] + (1.f - lb[4 + i]) * sigmoidf_(v1[i])); }
;                     } else if (mode == 3) {
.LBB0_253:
	s_andn2_b64 vcc, exec, s[12:13]
	s_cbranch_vccnz .LBB0_255
	v_mul_f32_e32 v130, 0xbfb8aa3b, v10
	v_mul_f32_e32 v132, 0xbfb8aa3b, v2
	v_exp_f32_e32 v130, v130
	v_exp_f32_e32 v132, v132
	v_add_f32_e32 v130, 1.0, v130
	v_add_f32_e32 v132, 1.0, v132
	v_rcp_f32_e32 v130, v130
	v_rcp_f32_e32 v132, v132
	v_fma_f32 v130, v130, v200, v196
	v_fma_f32 v132, v132, v199, v195
	v_max_f32_e32 v130, s91, v130
	v_max_f32_e32 v132, s91, v132
	v_log_f32_e32 v130, v130
	v_log_f32_e32 v132, v132
	v_mul_f32_e32 v196, 0x3f317217, v130
	v_mul_f32_e32 v195, 0x3f317217, v132
	v_fma_f32 v196, v130, s92, -v196
	v_fma_f32 v195, v132, s92, -v195
	v_fmac_f32_e32 v196, 0x3377d1cf, v130
	v_fmac_f32_e32 v195, 0x3377d1cf, v132
	v_fma_f32 v130, v130, s92, v196
	v_fma_f32 v132, v132, s92, v195
	v_mul_f32_e32 v131, 0xbfb8aa3b, v11
	v_mul_f32_e32 v172, 0xbfb8aa3b, v4
	v_exp_f32_e32 v131, v131
	v_exp_f32_e32 v172, v172
	v_add_f32_e32 v131, 1.0, v131
	v_add_f32_e32 v172, 1.0, v172
	v_rcp_f32_e32 v131, v131
	v_rcp_f32_e32 v172, v172
	v_fma_f32 v131, v131, v198, v193
	v_fma_f32 v172, v172, v192, v187
	v_max_f32_e32 v131, s91, v131
	v_max_f32_e32 v172, s91, v172
	v_log_f32_e32 v131, v131
	v_log_f32_e32 v172, v172
	v_mul_f32_e32 v193, 0x3f317217, v131
	v_mul_f32_e32 v187, 0x3f317217, v172
	v_fma_f32 v193, v131, s92, -v193
	v_fma_f32 v187, v172, s92, -v187
	v_fmac_f32_e32 v193, 0x3377d1cf, v131
	v_fmac_f32_e32 v187, 0x3377d1cf, v172
	v_fma_f32 v131, v131, s92, v193
	v_fma_f32 v172, v172, s92, v187
	v_mul_f32_e32 v133, 0xbfb8aa3b, v3
	v_mul_f32_e32 v170, 0xbfb8aa3b, v12
	v_exp_f32_e32 v133, v133
	v_exp_f32_e32 v170, v170
	v_add_f32_e32 v133, 1.0, v133
	v_add_f32_e32 v170, 1.0, v170
	v_rcp_f32_e32 v133, v133
	v_rcp_f32_e32 v170, v170
	v_fma_f32 v133, v133, v197, v191
	v_fma_f32 v170, v170, v194, v189
	v_max_f32_e32 v133, s91, v133
	v_max_f32_e32 v170, s91, v170
	v_log_f32_e32 v133, v133
	v_log_f32_e32 v170, v170
	v_mul_f32_e32 v191, 0x3f317217, v133
	v_mul_f32_e32 v189, 0x3f317217, v170
	v_fma_f32 v191, v133, s92, -v191
	v_fma_f32 v189, v170, s92, -v189
	v_fmac_f32_e32 v191, 0x3377d1cf, v133
	v_fmac_f32_e32 v189, 0x3377d1cf, v170
	v_fma_f32 v133, v133, s92, v191
	v_fma_f32 v170, v170, s92, v189
	v_mul_f32_e32 v171, 0xbfb8aa3b, v13
	v_mul_f32_e32 v173, 0xbfb8aa3b, v5
	v_exp_f32_e32 v171, v171
	v_exp_f32_e32 v173, v173
	v_add_f32_e32 v171, 1.0, v171
	v_add_f32_e32 v173, 1.0, v173
	v_rcp_f32_e32 v171, v171
	v_rcp_f32_e32 v173, v173
	v_fma_f32 v171, v171, v190, v186
	v_fma_f32 v173, v173, v188, v185
	v_max_f32_e32 v171, s91, v171
	v_max_f32_e32 v173, s91, v173
	v_log_f32_e32 v171, v171
	v_log_f32_e32 v173, v173
	v_mul_f32_e32 v186, 0x3f317217, v171
	v_mul_f32_e32 v185, 0x3f317217, v173
	v_fma_f32 v186, v171, s92, -v186
	v_fma_f32 v185, v173, s92, -v185
	v_fmac_f32_e32 v186, 0x3377d1cf, v171
	v_fmac_f32_e32 v185, 0x3377d1cf, v173
	v_fma_f32 v171, v171, s92, v186
	v_fma_f32 v173, v173, s92, v185
